# SwiGLU GEMM epilogue: non-transcendental arithmetic done with packed f32 VALU ops (128 fewer VALU per tile-wave), on top of v14
# baseline (speedup 1.0000x reference)
.LBB0_297:
	s_mov_b32 s98, 0xbfb8aa3b
	v_pk_mul_f32 v[240:241], v[126:127], s[98:99] op_sel_hi:[1,0]
	v_pk_mul_f32 v[242:243], v[128:129], s[98:99] op_sel_hi:[1,0]
	v_pk_mul_f32 v[244:245], v[122:123], s[98:99] op_sel_hi:[1,0]
	v_pk_mul_f32 v[246:247], v[124:125], s[98:99] op_sel_hi:[1,0]
	v_exp_f32_e32 v240, v240
	v_exp_f32_e32 v241, v241
	v_exp_f32_e32 v242, v242
	v_exp_f32_e32 v243, v243
	v_exp_f32_e32 v244, v244
	v_exp_f32_e32 v245, v245
	v_exp_f32_e32 v246, v246
	v_exp_f32_e32 v247, v247
	v_pk_add_f32 v[240:241], v[240:241], 1.0 op_sel_hi:[1,0]
	v_pk_add_f32 v[242:243], v[242:243], 1.0 op_sel_hi:[1,0]
	v_pk_add_f32 v[244:245], v[244:245], 1.0 op_sel_hi:[1,0]
	v_pk_add_f32 v[246:247], v[246:247], 1.0 op_sel_hi:[1,0]
	v_rcp_f32_e32 v240, v240
	v_rcp_f32_e32 v241, v241
	v_rcp_f32_e32 v242, v242
	v_rcp_f32_e32 v243, v243
	v_rcp_f32_e32 v244, v244
	v_rcp_f32_e32 v245, v245
	v_rcp_f32_e32 v246, v246
	v_rcp_f32_e32 v247, v247
	v_pk_mul_f32 v[240:241], v[126:127], v[240:241]
	v_pk_mul_f32 v[242:243], v[128:129], v[242:243]
	v_pk_mul_f32 v[244:245], v[122:123], v[244:245]
	v_pk_mul_f32 v[246:247], v[124:125], v[246:247]
	v_pk_mul_f32 v[240:241], v[240:241], v[118:119]
	v_pk_mul_f32 v[242:243], v[242:243], v[120:121]
	v_pk_mul_f32 v[244:245], v[244:245], v[114:115]
	v_pk_mul_f32 v[246:247], v[246:247], v[116:117]
	v_lshl_or_b32 v156, s2, 7, v150
	v_lshl_add_u32 v154, s22, 8, v148
	v_ashrrev_i32_e32 v157, 31, v156
	v_mov_b64_e32 v[146:147], s[8:9]
	v_mad_i64_i32 v[158:159], s[24:25], v154, s46, v[146:147]
	v_lshlrev_b64 v[114:115], 1, v[156:157]
	v_lshl_add_u64 v[120:121], v[158:159], 0, v[114:115]
	v_cvt_pk_bf16_f32 v116, v240, v241
	v_cvt_pk_bf16_f32 v117, v242, v243
	v_cvt_pk_bf16_f32 v118, v244, v245
	v_cvt_pk_bf16_f32 v119, v246, v247
	global_store_dwordx4 v[120:121], v[116:119], off
	v_pk_mul_f32 v[240:241], v[110:111], s[98:99] op_sel_hi:[1,0]
	v_pk_mul_f32 v[242:243], v[112:113], s[98:99] op_sel_hi:[1,0]
	v_pk_mul_f32 v[244:245], v[106:107], s[98:99] op_sel_hi:[1,0]
	v_pk_mul_f32 v[246:247], v[108:109], s[98:99] op_sel_hi:[1,0]
	v_exp_f32_e32 v240, v240
	v_exp_f32_e32 v241, v241
	v_exp_f32_e32 v242, v242
	v_exp_f32_e32 v243, v243
	v_exp_f32_e32 v244, v244
	v_exp_f32_e32 v245, v245
	v_exp_f32_e32 v246, v246
	v_exp_f32_e32 v247, v247
	v_pk_add_f32 v[240:241], v[240:241], 1.0 op_sel_hi:[1,0]
	v_pk_add_f32 v[242:243], v[242:243], 1.0 op_sel_hi:[1,0]
	v_pk_add_f32 v[244:245], v[244:245], 1.0 op_sel_hi:[1,0]
	v_pk_add_f32 v[246:247], v[246:247], 1.0 op_sel_hi:[1,0]
	v_rcp_f32_e32 v240, v240
	v_rcp_f32_e32 v241, v241
	v_rcp_f32_e32 v242, v242
	v_rcp_f32_e32 v243, v243
	v_rcp_f32_e32 v244, v244
	v_rcp_f32_e32 v245, v245
	v_rcp_f32_e32 v246, v246
	v_rcp_f32_e32 v247, v247
	v_pk_mul_f32 v[240:241], v[110:111], v[240:241]
	v_pk_mul_f32 v[242:243], v[112:113], v[242:243]
	v_pk_mul_f32 v[244:245], v[106:107], v[244:245]
	v_pk_mul_f32 v[246:247], v[108:109], v[246:247]
	v_pk_mul_f32 v[240:241], v[240:241], v[102:103]
	v_pk_mul_f32 v[242:243], v[242:243], v[104:105]
	v_pk_mul_f32 v[244:245], v[244:245], v[98:99]
	v_pk_mul_f32 v[246:247], v[246:247], v[100:101]
	s_andn2_b64 vcc, exec, s[4:5]
	s_mov_b64 s[4:5], -1
	v_or_b32_e32 v118, 16, v154
	v_mad_i64_i32 v[116:117], s[24:25], v118, s46, v[146:147]
	v_lshl_add_u64 v[102:103], v[116:117], 0, v[114:115]
	v_cvt_pk_bf16_f32 v98, v240, v241
	v_cvt_pk_bf16_f32 v99, v242, v243
	v_cvt_pk_bf16_f32 v100, v244, v245
	v_cvt_pk_bf16_f32 v101, v246, v247
	global_store_dwordx4 v[102:103], v[98:101], off
	v_pk_mul_f32 v[240:241], v[94:95], s[98:99] op_sel_hi:[1,0]
	v_pk_mul_f32 v[242:243], v[96:97], s[98:99] op_sel_hi:[1,0]
	v_pk_mul_f32 v[244:245], v[90:91], s[98:99] op_sel_hi:[1,0]
	v_pk_mul_f32 v[246:247], v[92:93], s[98:99] op_sel_hi:[1,0]
	v_exp_f32_e32 v240, v240
	v_exp_f32_e32 v241, v241
	v_exp_f32_e32 v242, v242
	v_exp_f32_e32 v243, v243
	v_exp_f32_e32 v244, v244
	v_exp_f32_e32 v245, v245
	v_exp_f32_e32 v246, v246
	v_exp_f32_e32 v247, v247
	v_pk_add_f32 v[240:241], v[240:241], 1.0 op_sel_hi:[1,0]
	v_pk_add_f32 v[242:243], v[242:243], 1.0 op_sel_hi:[1,0]
	v_pk_add_f32 v[244:245], v[244:245], 1.0 op_sel_hi:[1,0]
	v_pk_add_f32 v[246:247], v[246:247], 1.0 op_sel_hi:[1,0]
	v_rcp_f32_e32 v240, v240
	v_rcp_f32_e32 v241, v241
	v_rcp_f32_e32 v242, v242
	v_rcp_f32_e32 v243, v243
	v_rcp_f32_e32 v244, v244
	v_rcp_f32_e32 v245, v245
	v_rcp_f32_e32 v246, v246
	v_rcp_f32_e32 v247, v247
	v_pk_mul_f32 v[240:241], v[94:95], v[240:241]
	v_pk_mul_f32 v[242:243], v[96:97], v[242:243]
	v_pk_mul_f32 v[244:245], v[90:91], v[244:245]
	v_pk_mul_f32 v[246:247], v[92:93], v[246:247]
	v_pk_mul_f32 v[240:241], v[240:241], v[86:87]
	v_pk_mul_f32 v[242:243], v[242:243], v[88:89]
	v_pk_mul_f32 v[244:245], v[244:245], v[82:83]
	v_pk_mul_f32 v[246:247], v[246:247], v[84:85]
	v_or_b32_e32 v100, 32, v154
	v_mad_i64_i32 v[98:99], s[24:25], v100, s46, v[146:147]
	v_lshl_add_u64 v[86:87], v[98:99], 0, v[114:115]
	v_cvt_pk_bf16_f32 v82, v240, v241
	v_cvt_pk_bf16_f32 v83, v242, v243
	v_cvt_pk_bf16_f32 v84, v244, v245
	v_cvt_pk_bf16_f32 v85, v246, v247
	global_store_dwordx4 v[86:87], v[82:85], off
	v_pk_mul_f32 v[240:241], v[78:79], s[98:99] op_sel_hi:[1,0]
	v_pk_mul_f32 v[242:243], v[80:81], s[98:99] op_sel_hi:[1,0]
	v_pk_mul_f32 v[244:245], v[74:75], s[98:99] op_sel_hi:[1,0]
	v_pk_mul_f32 v[246:247], v[76:77], s[98:99] op_sel_hi:[1,0]
	v_exp_f32_e32 v240, v240
	v_exp_f32_e32 v241, v241
	v_exp_f32_e32 v242, v242
	v_exp_f32_e32 v243, v243
	v_exp_f32_e32 v244, v244
	v_exp_f32_e32 v245, v245
	v_exp_f32_e32 v246, v246
	v_exp_f32_e32 v247, v247
	v_pk_add_f32 v[240:241], v[240:241], 1.0 op_sel_hi:[1,0]
	v_pk_add_f32 v[242:243], v[242:243], 1.0 op_sel_hi:[1,0]
	v_pk_add_f32 v[244:245], v[244:245], 1.0 op_sel_hi:[1,0]
	v_pk_add_f32 v[246:247], v[246:247], 1.0 op_sel_hi:[1,0]
	v_rcp_f32_e32 v240, v240
	v_rcp_f32_e32 v241, v241
	v_rcp_f32_e32 v242, v242
	v_rcp_f32_e32 v243, v243
	v_rcp_f32_e32 v244, v244
	v_rcp_f32_e32 v245, v245
	v_rcp_f32_e32 v246, v246
	v_rcp_f32_e32 v247, v247
	v_pk_mul_f32 v[240:241], v[78:79], v[240:241]
	v_pk_mul_f32 v[242:243], v[80:81], v[242:243]
	v_pk_mul_f32 v[244:245], v[74:75], v[244:245]
	v_pk_mul_f32 v[246:247], v[76:77], v[246:247]
	v_pk_mul_f32 v[240:241], v[240:241], v[70:71]
	v_pk_mul_f32 v[242:243], v[242:243], v[72:73]
	v_pk_mul_f32 v[244:245], v[244:245], v[66:67]
	v_pk_mul_f32 v[246:247], v[246:247], v[68:69]
	v_or_b32_e32 v84, 48, v154
	v_mad_i64_i32 v[82:83], s[24:25], v84, s46, v[146:147]
	v_lshl_add_u64 v[70:71], v[82:83], 0, v[114:115]
	v_cvt_pk_bf16_f32 v66, v240, v241
	v_cvt_pk_bf16_f32 v67, v242, v243
	v_cvt_pk_bf16_f32 v68, v244, v245
	v_cvt_pk_bf16_f32 v69, v246, v247
	global_store_dwordx4 v[70:71], v[66:69], off
	v_pk_mul_f32 v[240:241], v[62:63], s[98:99] op_sel_hi:[1,0]
	v_pk_mul_f32 v[242:243], v[64:65], s[98:99] op_sel_hi:[1,0]
	v_pk_mul_f32 v[244:245], v[58:59], s[98:99] op_sel_hi:[1,0]
	v_pk_mul_f32 v[246:247], v[60:61], s[98:99] op_sel_hi:[1,0]
	v_exp_f32_e32 v240, v240
	v_exp_f32_e32 v241, v241
	v_exp_f32_e32 v242, v242
	v_exp_f32_e32 v243, v243
	v_exp_f32_e32 v244, v244
	v_exp_f32_e32 v245, v245
	v_exp_f32_e32 v246, v246
	v_exp_f32_e32 v247, v247
	v_pk_add_f32 v[240:241], v[240:241], 1.0 op_sel_hi:[1,0]
	v_pk_add_f32 v[242:243], v[242:243], 1.0 op_sel_hi:[1,0]
	v_pk_add_f32 v[244:245], v[244:245], 1.0 op_sel_hi:[1,0]
	v_pk_add_f32 v[246:247], v[246:247], 1.0 op_sel_hi:[1,0]
	v_rcp_f32_e32 v240, v240
	v_rcp_f32_e32 v241, v241
	v_rcp_f32_e32 v242, v242
	v_rcp_f32_e32 v243, v243
	v_rcp_f32_e32 v244, v244
	v_rcp_f32_e32 v245, v245
	v_rcp_f32_e32 v246, v246
	v_rcp_f32_e32 v247, v247
	v_pk_mul_f32 v[240:241], v[62:63], v[240:241]
	v_pk_mul_f32 v[242:243], v[64:65], v[242:243]
	v_pk_mul_f32 v[244:245], v[58:59], v[244:245]
	v_pk_mul_f32 v[246:247], v[60:61], v[246:247]
	v_pk_mul_f32 v[240:241], v[240:241], v[54:55]
	v_pk_mul_f32 v[242:243], v[242:243], v[56:57]
	v_pk_mul_f32 v[244:245], v[244:245], v[50:51]
	v_pk_mul_f32 v[246:247], v[246:247], v[52:53]
	v_add_u32_e32 v68, 0x80, v154
	v_mad_i64_i32 v[66:67], s[24:25], v68, s46, v[146:147]
	v_lshl_add_u64 v[54:55], v[66:67], 0, v[114:115]
	v_cvt_pk_bf16_f32 v50, v240, v241
	v_cvt_pk_bf16_f32 v51, v242, v243
	v_cvt_pk_bf16_f32 v52, v244, v245
	v_cvt_pk_bf16_f32 v53, v246, v247
	global_store_dwordx4 v[54:55], v[50:53], off
	v_pk_mul_f32 v[240:241], v[46:47], s[98:99] op_sel_hi:[1,0]
	v_pk_mul_f32 v[242:243], v[48:49], s[98:99] op_sel_hi:[1,0]
	v_pk_mul_f32 v[244:245], v[42:43], s[98:99] op_sel_hi:[1,0]
	v_pk_mul_f32 v[246:247], v[44:45], s[98:99] op_sel_hi:[1,0]
	v_exp_f32_e32 v240, v240
	v_exp_f32_e32 v241, v241
	v_exp_f32_e32 v242, v242
	v_exp_f32_e32 v243, v243
	v_exp_f32_e32 v244, v244
	v_exp_f32_e32 v245, v245
	v_exp_f32_e32 v246, v246
	v_exp_f32_e32 v247, v247
	v_pk_add_f32 v[240:241], v[240:241], 1.0 op_sel_hi:[1,0]
	v_pk_add_f32 v[242:243], v[242:243], 1.0 op_sel_hi:[1,0]
	v_pk_add_f32 v[244:245], v[244:245], 1.0 op_sel_hi:[1,0]
	v_pk_add_f32 v[246:247], v[246:247], 1.0 op_sel_hi:[1,0]
	v_rcp_f32_e32 v240, v240
	v_rcp_f32_e32 v241, v241
	v_rcp_f32_e32 v242, v242
	v_rcp_f32_e32 v243, v243
	v_rcp_f32_e32 v244, v244
	v_rcp_f32_e32 v245, v245
	v_rcp_f32_e32 v246, v246
	v_rcp_f32_e32 v247, v247
	v_pk_mul_f32 v[240:241], v[46:47], v[240:241]
	v_pk_mul_f32 v[242:243], v[48:49], v[242:243]
	v_pk_mul_f32 v[244:245], v[42:43], v[244:245]
	v_pk_mul_f32 v[246:247], v[44:45], v[246:247]
	v_pk_mul_f32 v[240:241], v[240:241], v[38:39]
	v_pk_mul_f32 v[242:243], v[242:243], v[40:41]
	v_pk_mul_f32 v[244:245], v[244:245], v[34:35]
	v_pk_mul_f32 v[246:247], v[246:247], v[36:37]
	v_add_u32_e32 v52, 0x90, v154
	v_mad_i64_i32 v[50:51], s[24:25], v52, s46, v[146:147]
	v_lshl_add_u64 v[38:39], v[50:51], 0, v[114:115]
	v_cvt_pk_bf16_f32 v34, v240, v241
	v_cvt_pk_bf16_f32 v35, v242, v243
	v_cvt_pk_bf16_f32 v36, v244, v245
	v_cvt_pk_bf16_f32 v37, v246, v247
	global_store_dwordx4 v[38:39], v[34:37], off
	v_pk_mul_f32 v[240:241], v[30:31], s[98:99] op_sel_hi:[1,0]
	v_pk_mul_f32 v[242:243], v[32:33], s[98:99] op_sel_hi:[1,0]
	v_pk_mul_f32 v[244:245], v[26:27], s[98:99] op_sel_hi:[1,0]
	v_pk_mul_f32 v[246:247], v[28:29], s[98:99] op_sel_hi:[1,0]
	v_exp_f32_e32 v240, v240
	v_exp_f32_e32 v241, v241
	v_exp_f32_e32 v242, v242
	v_exp_f32_e32 v243, v243
	v_exp_f32_e32 v244, v244
	v_exp_f32_e32 v245, v245
	v_exp_f32_e32 v246, v246
	v_exp_f32_e32 v247, v247
	v_pk_add_f32 v[240:241], v[240:241], 1.0 op_sel_hi:[1,0]
	v_pk_add_f32 v[242:243], v[242:243], 1.0 op_sel_hi:[1,0]
	v_pk_add_f32 v[244:245], v[244:245], 1.0 op_sel_hi:[1,0]
	v_pk_add_f32 v[246:247], v[246:247], 1.0 op_sel_hi:[1,0]
	v_rcp_f32_e32 v240, v240
	v_rcp_f32_e32 v241, v241
	v_rcp_f32_e32 v242, v242
	v_rcp_f32_e32 v243, v243
	v_rcp_f32_e32 v244, v244
	v_rcp_f32_e32 v245, v245
	v_rcp_f32_e32 v246, v246
	v_rcp_f32_e32 v247, v247
	v_pk_mul_f32 v[240:241], v[30:31], v[240:241]
	v_pk_mul_f32 v[242:243], v[32:33], v[242:243]
	v_pk_mul_f32 v[244:245], v[26:27], v[244:245]
	v_pk_mul_f32 v[246:247], v[28:29], v[246:247]
	v_pk_mul_f32 v[240:241], v[240:241], v[22:23]
	v_pk_mul_f32 v[242:243], v[242:243], v[24:25]
	v_pk_mul_f32 v[244:245], v[244:245], v[18:19]
	v_pk_mul_f32 v[246:247], v[246:247], v[20:21]
	v_add_u32_e32 v36, 0xa0, v154
	v_mad_i64_i32 v[34:35], s[24:25], v36, s46, v[146:147]
	v_lshl_add_u64 v[22:23], v[34:35], 0, v[114:115]
	v_cvt_pk_bf16_f32 v18, v240, v241
	v_cvt_pk_bf16_f32 v19, v242, v243
	v_cvt_pk_bf16_f32 v20, v244, v245
	v_cvt_pk_bf16_f32 v21, v246, v247
	global_store_dwordx4 v[22:23], v[18:21], off
	v_pk_mul_f32 v[240:241], v[14:15], s[98:99] op_sel_hi:[1,0]
	v_pk_mul_f32 v[242:243], v[16:17], s[98:99] op_sel_hi:[1,0]
	v_pk_mul_f32 v[244:245], v[10:11], s[98:99] op_sel_hi:[1,0]
	v_pk_mul_f32 v[246:247], v[12:13], s[98:99] op_sel_hi:[1,0]
	v_exp_f32_e32 v240, v240
	v_exp_f32_e32 v241, v241
	v_exp_f32_e32 v242, v242
	v_exp_f32_e32 v243, v243
	v_exp_f32_e32 v244, v244
	v_exp_f32_e32 v245, v245
	v_exp_f32_e32 v246, v246
	v_exp_f32_e32 v247, v247
	v_pk_add_f32 v[240:241], v[240:241], 1.0 op_sel_hi:[1,0]
	v_pk_add_f32 v[242:243], v[242:243], 1.0 op_sel_hi:[1,0]
	v_pk_add_f32 v[244:245], v[244:245], 1.0 op_sel_hi:[1,0]
	v_pk_add_f32 v[246:247], v[246:247], 1.0 op_sel_hi:[1,0]
	v_rcp_f32_e32 v240, v240
	v_rcp_f32_e32 v241, v241
	v_rcp_f32_e32 v242, v242
	v_rcp_f32_e32 v243, v243
	v_rcp_f32_e32 v244, v244
	v_rcp_f32_e32 v245, v245
	v_rcp_f32_e32 v246, v246
	v_rcp_f32_e32 v247, v247
	v_pk_mul_f32 v[240:241], v[14:15], v[240:241]
	v_pk_mul_f32 v[242:243], v[16:17], v[242:243]
	v_pk_mul_f32 v[244:245], v[10:11], v[244:245]
	v_pk_mul_f32 v[246:247], v[12:13], v[246:247]
	v_pk_mul_f32 v[240:241], v[240:241], v[6:7]
	v_pk_mul_f32 v[242:243], v[242:243], v[8:9]
	v_pk_mul_f32 v[244:245], v[244:245], v[2:3]
	v_pk_mul_f32 v[246:247], v[246:247], v[4:5]
	v_add_u32_e32 v20, 0xb0, v154
	v_mad_i64_i32 v[18:19], s[24:25], v20, s46, v[146:147]
	v_lshl_add_u64 v[6:7], v[18:19], 0, v[114:115]
	v_cvt_pk_bf16_f32 v2, v240, v241
	v_cvt_pk_bf16_f32 v3, v242, v243
	v_cvt_pk_bf16_f32 v4, v244, v245
	v_cvt_pk_bf16_f32 v5, v246, v247
	global_store_dwordx4 v[6:7], v[2:5], off
	s_cbranch_vccnz .LBB0_286
	s_andn2_b64 vcc, exec, s[0:1]
	s_cbranch_vccnz .LBB0_285
	s_barrier
	s_branch .LBB0_285

.LBB0_2489:
	s_mov_b32 s98, 0xbfb8aa3b
	v_pk_mul_f32 v[240:241], v[126:127], s[98:99] op_sel_hi:[1,0]
	v_pk_mul_f32 v[242:243], v[128:129], s[98:99] op_sel_hi:[1,0]
	v_pk_mul_f32 v[244:245], v[122:123], s[98:99] op_sel_hi:[1,0]
	v_pk_mul_f32 v[246:247], v[124:125], s[98:99] op_sel_hi:[1,0]
	v_exp_f32_e32 v240, v240
	v_exp_f32_e32 v241, v241
	v_exp_f32_e32 v242, v242
	v_exp_f32_e32 v243, v243
	v_exp_f32_e32 v244, v244
	v_exp_f32_e32 v245, v245
	v_exp_f32_e32 v246, v246
	v_exp_f32_e32 v247, v247
	v_pk_add_f32 v[240:241], v[240:241], 1.0 op_sel_hi:[1,0]
	v_pk_add_f32 v[242:243], v[242:243], 1.0 op_sel_hi:[1,0]
	v_pk_add_f32 v[244:245], v[244:245], 1.0 op_sel_hi:[1,0]
	v_pk_add_f32 v[246:247], v[246:247], 1.0 op_sel_hi:[1,0]
	v_rcp_f32_e32 v240, v240
	v_rcp_f32_e32 v241, v241
	v_rcp_f32_e32 v242, v242
	v_rcp_f32_e32 v243, v243
	v_rcp_f32_e32 v244, v244
	v_rcp_f32_e32 v245, v245
	v_rcp_f32_e32 v246, v246
	v_rcp_f32_e32 v247, v247
	v_pk_mul_f32 v[240:241], v[126:127], v[240:241]
	v_pk_mul_f32 v[242:243], v[128:129], v[242:243]
	v_pk_mul_f32 v[244:245], v[122:123], v[244:245]
	v_pk_mul_f32 v[246:247], v[124:125], v[246:247]
	v_pk_mul_f32 v[240:241], v[240:241], v[118:119]
	v_pk_mul_f32 v[242:243], v[242:243], v[120:121]
	v_pk_mul_f32 v[244:245], v[244:245], v[114:115]
	v_pk_mul_f32 v[246:247], v[246:247], v[116:117]
	v_lshl_or_b32 v156, s2, 7, v150
	v_lshl_add_u32 v154, s22, 8, v148
	v_ashrrev_i32_e32 v157, 31, v156
	v_mov_b64_e32 v[146:147], s[8:9]
	v_mad_i64_i32 v[158:159], s[24:25], v154, s47, v[146:147]
	v_lshlrev_b64 v[114:115], 1, v[156:157]
	v_lshl_add_u64 v[120:121], v[158:159], 0, v[114:115]
	v_cvt_pk_bf16_f32 v116, v240, v241
	v_cvt_pk_bf16_f32 v117, v242, v243
	v_cvt_pk_bf16_f32 v118, v244, v245
	v_cvt_pk_bf16_f32 v119, v246, v247
	global_store_dwordx4 v[120:121], v[116:119], off
	v_pk_mul_f32 v[240:241], v[110:111], s[98:99] op_sel_hi:[1,0]
	v_pk_mul_f32 v[242:243], v[112:113], s[98:99] op_sel_hi:[1,0]
	v_pk_mul_f32 v[244:245], v[106:107], s[98:99] op_sel_hi:[1,0]
	v_pk_mul_f32 v[246:247], v[108:109], s[98:99] op_sel_hi:[1,0]
	v_exp_f32_e32 v240, v240
	v_exp_f32_e32 v241, v241
	v_exp_f32_e32 v242, v242
	v_exp_f32_e32 v243, v243
	v_exp_f32_e32 v244, v244
	v_exp_f32_e32 v245, v245
	v_exp_f32_e32 v246, v246
	v_exp_f32_e32 v247, v247
	v_pk_add_f32 v[240:241], v[240:241], 1.0 op_sel_hi:[1,0]
	v_pk_add_f32 v[242:243], v[242:243], 1.0 op_sel_hi:[1,0]
	v_pk_add_f32 v[244:245], v[244:245], 1.0 op_sel_hi:[1,0]
	v_pk_add_f32 v[246:247], v[246:247], 1.0 op_sel_hi:[1,0]
	v_rcp_f32_e32 v240, v240
	v_rcp_f32_e32 v241, v241
	v_rcp_f32_e32 v242, v242
	v_rcp_f32_e32 v243, v243
	v_rcp_f32_e32 v244, v244
	v_rcp_f32_e32 v245, v245
	v_rcp_f32_e32 v246, v246
	v_rcp_f32_e32 v247, v247
	v_pk_mul_f32 v[240:241], v[110:111], v[240:241]
	v_pk_mul_f32 v[242:243], v[112:113], v[242:243]
	v_pk_mul_f32 v[244:245], v[106:107], v[244:245]
	v_pk_mul_f32 v[246:247], v[108:109], v[246:247]
	v_pk_mul_f32 v[240:241], v[240:241], v[102:103]
	v_pk_mul_f32 v[242:243], v[242:243], v[104:105]
	v_pk_mul_f32 v[244:245], v[244:245], v[98:99]
	v_pk_mul_f32 v[246:247], v[246:247], v[100:101]
	s_andn2_b64 vcc, exec, s[4:5]
	s_mov_b64 s[4:5], -1
	v_or_b32_e32 v118, 16, v154
	v_mad_i64_i32 v[116:117], s[24:25], v118, s47, v[146:147]
	v_lshl_add_u64 v[102:103], v[116:117], 0, v[114:115]
	v_cvt_pk_bf16_f32 v98, v240, v241
	v_cvt_pk_bf16_f32 v99, v242, v243
	v_cvt_pk_bf16_f32 v100, v244, v245
	v_cvt_pk_bf16_f32 v101, v246, v247
	global_store_dwordx4 v[102:103], v[98:101], off
	v_pk_mul_f32 v[240:241], v[94:95], s[98:99] op_sel_hi:[1,0]
	v_pk_mul_f32 v[242:243], v[96:97], s[98:99] op_sel_hi:[1,0]
	v_pk_mul_f32 v[244:245], v[90:91], s[98:99] op_sel_hi:[1,0]
	v_pk_mul_f32 v[246:247], v[92:93], s[98:99] op_sel_hi:[1,0]
	v_exp_f32_e32 v240, v240
	v_exp_f32_e32 v241, v241
	v_exp_f32_e32 v242, v242
	v_exp_f32_e32 v243, v243
	v_exp_f32_e32 v244, v244
	v_exp_f32_e32 v245, v245
	v_exp_f32_e32 v246, v246
	v_exp_f32_e32 v247, v247
	v_pk_add_f32 v[240:241], v[240:241], 1.0 op_sel_hi:[1,0]
	v_pk_add_f32 v[242:243], v[242:243], 1.0 op_sel_hi:[1,0]
	v_pk_add_f32 v[244:245], v[244:245], 1.0 op_sel_hi:[1,0]
	v_pk_add_f32 v[246:247], v[246:247], 1.0 op_sel_hi:[1,0]
	v_rcp_f32_e32 v240, v240
	v_rcp_f32_e32 v241, v241
	v_rcp_f32_e32 v242, v242
	v_rcp_f32_e32 v243, v243
	v_rcp_f32_e32 v244, v244
	v_rcp_f32_e32 v245, v245
	v_rcp_f32_e32 v246, v246
	v_rcp_f32_e32 v247, v247
	v_pk_mul_f32 v[240:241], v[94:95], v[240:241]
	v_pk_mul_f32 v[242:243], v[96:97], v[242:243]
	v_pk_mul_f32 v[244:245], v[90:91], v[244:245]
	v_pk_mul_f32 v[246:247], v[92:93], v[246:247]
	v_pk_mul_f32 v[240:241], v[240:241], v[86:87]
	v_pk_mul_f32 v[242:243], v[242:243], v[88:89]
	v_pk_mul_f32 v[244:245], v[244:245], v[82:83]
	v_pk_mul_f32 v[246:247], v[246:247], v[84:85]
	v_or_b32_e32 v100, 32, v154
	v_mad_i64_i32 v[98:99], s[24:25], v100, s47, v[146:147]
	v_lshl_add_u64 v[86:87], v[98:99], 0, v[114:115]
	v_cvt_pk_bf16_f32 v82, v240, v241
	v_cvt_pk_bf16_f32 v83, v242, v243
	v_cvt_pk_bf16_f32 v84, v244, v245
	v_cvt_pk_bf16_f32 v85, v246, v247
	global_store_dwordx4 v[86:87], v[82:85], off
	v_pk_mul_f32 v[240:241], v[78:79], s[98:99] op_sel_hi:[1,0]
	v_pk_mul_f32 v[242:243], v[80:81], s[98:99] op_sel_hi:[1,0]
	v_pk_mul_f32 v[244:245], v[74:75], s[98:99] op_sel_hi:[1,0]
	v_pk_mul_f32 v[246:247], v[76:77], s[98:99] op_sel_hi:[1,0]
	v_exp_f32_e32 v240, v240
	v_exp_f32_e32 v241, v241
	v_exp_f32_e32 v242, v242
	v_exp_f32_e32 v243, v243
	v_exp_f32_e32 v244, v244
	v_exp_f32_e32 v245, v245
	v_exp_f32_e32 v246, v246
	v_exp_f32_e32 v247, v247
	v_pk_add_f32 v[240:241], v[240:241], 1.0 op_sel_hi:[1,0]
	v_pk_add_f32 v[242:243], v[242:243], 1.0 op_sel_hi:[1,0]
	v_pk_add_f32 v[244:245], v[244:245], 1.0 op_sel_hi:[1,0]
	v_pk_add_f32 v[246:247], v[246:247], 1.0 op_sel_hi:[1,0]
	v_rcp_f32_e32 v240, v240
	v_rcp_f32_e32 v241, v241
	v_rcp_f32_e32 v242, v242
	v_rcp_f32_e32 v243, v243
	v_rcp_f32_e32 v244, v244
	v_rcp_f32_e32 v245, v245
	v_rcp_f32_e32 v246, v246
	v_rcp_f32_e32 v247, v247
	v_pk_mul_f32 v[240:241], v[78:79], v[240:241]
	v_pk_mul_f32 v[242:243], v[80:81], v[242:243]
	v_pk_mul_f32 v[244:245], v[74:75], v[244:245]
	v_pk_mul_f32 v[246:247], v[76:77], v[246:247]
	v_pk_mul_f32 v[240:241], v[240:241], v[70:71]
	v_pk_mul_f32 v[242:243], v[242:243], v[72:73]
	v_pk_mul_f32 v[244:245], v[244:245], v[66:67]
	v_pk_mul_f32 v[246:247], v[246:247], v[68:69]
	v_or_b32_e32 v84, 48, v154
	v_mad_i64_i32 v[82:83], s[24:25], v84, s47, v[146:147]
	v_lshl_add_u64 v[70:71], v[82:83], 0, v[114:115]
	v_cvt_pk_bf16_f32 v66, v240, v241
	v_cvt_pk_bf16_f32 v67, v242, v243
	v_cvt_pk_bf16_f32 v68, v244, v245
	v_cvt_pk_bf16_f32 v69, v246, v247
	global_store_dwordx4 v[70:71], v[66:69], off
	v_pk_mul_f32 v[240:241], v[62:63], s[98:99] op_sel_hi:[1,0]
	v_pk_mul_f32 v[242:243], v[64:65], s[98:99] op_sel_hi:[1,0]
	v_pk_mul_f32 v[244:245], v[58:59], s[98:99] op_sel_hi:[1,0]
	v_pk_mul_f32 v[246:247], v[60:61], s[98:99] op_sel_hi:[1,0]
	v_exp_f32_e32 v240, v240
	v_exp_f32_e32 v241, v241
	v_exp_f32_e32 v242, v242
	v_exp_f32_e32 v243, v243
	v_exp_f32_e32 v244, v244
	v_exp_f32_e32 v245, v245
	v_exp_f32_e32 v246, v246
	v_exp_f32_e32 v247, v247
	v_pk_add_f32 v[240:241], v[240:241], 1.0 op_sel_hi:[1,0]
	v_pk_add_f32 v[242:243], v[242:243], 1.0 op_sel_hi:[1,0]
	v_pk_add_f32 v[244:245], v[244:245], 1.0 op_sel_hi:[1,0]
	v_pk_add_f32 v[246:247], v[246:247], 1.0 op_sel_hi:[1,0]
	v_rcp_f32_e32 v240, v240
	v_rcp_f32_e32 v241, v241
	v_rcp_f32_e32 v242, v242
	v_rcp_f32_e32 v243, v243
	v_rcp_f32_e32 v244, v244
	v_rcp_f32_e32 v245, v245
	v_rcp_f32_e32 v246, v246
	v_rcp_f32_e32 v247, v247
	v_pk_mul_f32 v[240:241], v[62:63], v[240:241]
	v_pk_mul_f32 v[242:243], v[64:65], v[242:243]
	v_pk_mul_f32 v[244:245], v[58:59], v[244:245]
	v_pk_mul_f32 v[246:247], v[60:61], v[246:247]
	v_pk_mul_f32 v[240:241], v[240:241], v[54:55]
	v_pk_mul_f32 v[242:243], v[242:243], v[56:57]
	v_pk_mul_f32 v[244:245], v[244:245], v[50:51]
	v_pk_mul_f32 v[246:247], v[246:247], v[52:53]
	v_add_u32_e32 v68, 0x80, v154
	v_mad_i64_i32 v[66:67], s[24:25], v68, s47, v[146:147]
	v_lshl_add_u64 v[54:55], v[66:67], 0, v[114:115]
	v_cvt_pk_bf16_f32 v50, v240, v241
	v_cvt_pk_bf16_f32 v51, v242, v243
	v_cvt_pk_bf16_f32 v52, v244, v245
	v_cvt_pk_bf16_f32 v53, v246, v247
	global_store_dwordx4 v[54:55], v[50:53], off
	v_pk_mul_f32 v[240:241], v[46:47], s[98:99] op_sel_hi:[1,0]
	v_pk_mul_f32 v[242:243], v[48:49], s[98:99] op_sel_hi:[1,0]
	v_pk_mul_f32 v[244:245], v[42:43], s[98:99] op_sel_hi:[1,0]
	v_pk_mul_f32 v[246:247], v[44:45], s[98:99] op_sel_hi:[1,0]
	v_exp_f32_e32 v240, v240
	v_exp_f32_e32 v241, v241
	v_exp_f32_e32 v242, v242
	v_exp_f32_e32 v243, v243
	v_exp_f32_e32 v244, v244
	v_exp_f32_e32 v245, v245
	v_exp_f32_e32 v246, v246
	v_exp_f32_e32 v247, v247
	v_pk_add_f32 v[240:241], v[240:241], 1.0 op_sel_hi:[1,0]
	v_pk_add_f32 v[242:243], v[242:243], 1.0 op_sel_hi:[1,0]
	v_pk_add_f32 v[244:245], v[244:245], 1.0 op_sel_hi:[1,0]
	v_pk_add_f32 v[246:247], v[246:247], 1.0 op_sel_hi:[1,0]
	v_rcp_f32_e32 v240, v240
	v_rcp_f32_e32 v241, v241
	v_rcp_f32_e32 v242, v242
	v_rcp_f32_e32 v243, v243
	v_rcp_f32_e32 v244, v244
	v_rcp_f32_e32 v245, v245
	v_rcp_f32_e32 v246, v246
	v_rcp_f32_e32 v247, v247
	v_pk_mul_f32 v[240:241], v[46:47], v[240:241]
	v_pk_mul_f32 v[242:243], v[48:49], v[242:243]
	v_pk_mul_f32 v[244:245], v[42:43], v[244:245]
	v_pk_mul_f32 v[246:247], v[44:45], v[246:247]
	v_pk_mul_f32 v[240:241], v[240:241], v[38:39]
	v_pk_mul_f32 v[242:243], v[242:243], v[40:41]
	v_pk_mul_f32 v[244:245], v[244:245], v[34:35]
	v_pk_mul_f32 v[246:247], v[246:247], v[36:37]
	v_add_u32_e32 v52, 0x90, v154
	v_mad_i64_i32 v[50:51], s[24:25], v52, s47, v[146:147]
	v_lshl_add_u64 v[38:39], v[50:51], 0, v[114:115]
	v_cvt_pk_bf16_f32 v34, v240, v241
	v_cvt_pk_bf16_f32 v35, v242, v243
	v_cvt_pk_bf16_f32 v36, v244, v245
	v_cvt_pk_bf16_f32 v37, v246, v247
	global_store_dwordx4 v[38:39], v[34:37], off
	v_pk_mul_f32 v[240:241], v[30:31], s[98:99] op_sel_hi:[1,0]
	v_pk_mul_f32 v[242:243], v[32:33], s[98:99] op_sel_hi:[1,0]
	v_pk_mul_f32 v[244:245], v[26:27], s[98:99] op_sel_hi:[1,0]
	v_pk_mul_f32 v[246:247], v[28:29], s[98:99] op_sel_hi:[1,0]
	v_exp_f32_e32 v240, v240
	v_exp_f32_e32 v241, v241
	v_exp_f32_e32 v242, v242
	v_exp_f32_e32 v243, v243
	v_exp_f32_e32 v244, v244
	v_exp_f32_e32 v245, v245
	v_exp_f32_e32 v246, v246
	v_exp_f32_e32 v247, v247
	v_pk_add_f32 v[240:241], v[240:241], 1.0 op_sel_hi:[1,0]
	v_pk_add_f32 v[242:243], v[242:243], 1.0 op_sel_hi:[1,0]
	v_pk_add_f32 v[244:245], v[244:245], 1.0 op_sel_hi:[1,0]
	v_pk_add_f32 v[246:247], v[246:247], 1.0 op_sel_hi:[1,0]
	v_rcp_f32_e32 v240, v240
	v_rcp_f32_e32 v241, v241
	v_rcp_f32_e32 v242, v242
	v_rcp_f32_e32 v243, v243
	v_rcp_f32_e32 v244, v244
	v_rcp_f32_e32 v245, v245
	v_rcp_f32_e32 v246, v246
	v_rcp_f32_e32 v247, v247
	v_pk_mul_f32 v[240:241], v[30:31], v[240:241]
	v_pk_mul_f32 v[242:243], v[32:33], v[242:243]
	v_pk_mul_f32 v[244:245], v[26:27], v[244:245]
	v_pk_mul_f32 v[246:247], v[28:29], v[246:247]
	v_pk_mul_f32 v[240:241], v[240:241], v[22:23]
	v_pk_mul_f32 v[242:243], v[242:243], v[24:25]
	v_pk_mul_f32 v[244:245], v[244:245], v[18:19]
	v_pk_mul_f32 v[246:247], v[246:247], v[20:21]
	v_add_u32_e32 v36, 0xa0, v154
	v_mad_i64_i32 v[34:35], s[24:25], v36, s47, v[146:147]
	v_lshl_add_u64 v[22:23], v[34:35], 0, v[114:115]
	v_cvt_pk_bf16_f32 v18, v240, v241
	v_cvt_pk_bf16_f32 v19, v242, v243
	v_cvt_pk_bf16_f32 v20, v244, v245
	v_cvt_pk_bf16_f32 v21, v246, v247
	global_store_dwordx4 v[22:23], v[18:21], off
	v_pk_mul_f32 v[240:241], v[14:15], s[98:99] op_sel_hi:[1,0]
	v_pk_mul_f32 v[242:243], v[16:17], s[98:99] op_sel_hi:[1,0]
	v_pk_mul_f32 v[244:245], v[10:11], s[98:99] op_sel_hi:[1,0]
	v_pk_mul_f32 v[246:247], v[12:13], s[98:99] op_sel_hi:[1,0]
	v_exp_f32_e32 v240, v240
	v_exp_f32_e32 v241, v241
	v_exp_f32_e32 v242, v242
	v_exp_f32_e32 v243, v243
	v_exp_f32_e32 v244, v244
	v_exp_f32_e32 v245, v245
	v_exp_f32_e32 v246, v246
	v_exp_f32_e32 v247, v247
	v_pk_add_f32 v[240:241], v[240:241], 1.0 op_sel_hi:[1,0]
	v_pk_add_f32 v[242:243], v[242:243], 1.0 op_sel_hi:[1,0]
	v_pk_add_f32 v[244:245], v[244:245], 1.0 op_sel_hi:[1,0]
	v_pk_add_f32 v[246:247], v[246:247], 1.0 op_sel_hi:[1,0]
	v_rcp_f32_e32 v240, v240
	v_rcp_f32_e32 v241, v241
	v_rcp_f32_e32 v242, v242
	v_rcp_f32_e32 v243, v243
	v_rcp_f32_e32 v244, v244
	v_rcp_f32_e32 v245, v245
	v_rcp_f32_e32 v246, v246
	v_rcp_f32_e32 v247, v247
	v_pk_mul_f32 v[240:241], v[14:15], v[240:241]
	v_pk_mul_f32 v[242:243], v[16:17], v[242:243]
	v_pk_mul_f32 v[244:245], v[10:11], v[244:245]
	v_pk_mul_f32 v[246:247], v[12:13], v[246:247]
	v_pk_mul_f32 v[240:241], v[240:241], v[6:7]
	v_pk_mul_f32 v[242:243], v[242:243], v[8:9]
	v_pk_mul_f32 v[244:245], v[244:245], v[2:3]
	v_pk_mul_f32 v[246:247], v[246:247], v[4:5]
	v_add_u32_e32 v20, 0xb0, v154
	v_mad_i64_i32 v[18:19], s[24:25], v20, s47, v[146:147]
	v_lshl_add_u64 v[6:7], v[18:19], 0, v[114:115]
	v_cvt_pk_bf16_f32 v2, v240, v241
	v_cvt_pk_bf16_f32 v3, v242, v243
	v_cvt_pk_bf16_f32 v4, v244, v245
	v_cvt_pk_bf16_f32 v5, v246, v247
	global_store_dwordx4 v[6:7], v[2:5], off
	s_cbranch_vccnz .LBB0_2482
	s_andn2_b64 vcc, exec, s[0:1]
	s_cbranch_vccnz .LBB0_2481
	s_barrier
	s_branch .LBB0_2481
